# scan loader: y-reduce LDS reads issued at the top of the iteration into registers freed by the DMA path (latency overlapped with the store and load-issue part)
# baseline (speedup 1.0000x reference)
.LBB0_1104:
	s_waitcnt lgkmcnt(0)
	v_pk_add_f32 v[6:7], v[6:7], v[10:11]
	v_pk_add_f32 v[4:5], v[4:5], v[8:9]
	v_pk_add_f32 v[18:19], v[18:19], v[22:23]
	v_pk_add_f32 v[16:17], v[16:17], v[20:21]
	v_pk_add_f32 v[18:19], v[6:7], v[18:19]
	v_pk_add_f32 v[16:17], v[4:5], v[16:17]
	s_nop 1
	v_add_f32_dpp v16, v16, v16 quad_perm:[1,0,3,2] row_mask:0xf bank_mask:0xf bound_ctrl:1
	v_add_f32_dpp v17, v17, v17 quad_perm:[1,0,3,2] row_mask:0xf bank_mask:0xf bound_ctrl:1
	v_add_f32_dpp v18, v18, v18 quad_perm:[1,0,3,2] row_mask:0xf bank_mask:0xf bound_ctrl:1
	v_add_f32_dpp v19, v19, v19 quad_perm:[1,0,3,2] row_mask:0xf bank_mask:0xf bound_ctrl:1
	v_add_f32_dpp v16, v16, v16 quad_perm:[2,3,0,1] row_mask:0xf bank_mask:0xf bound_ctrl:1
	v_add_f32_dpp v17, v17, v17 quad_perm:[2,3,0,1] row_mask:0xf bank_mask:0xf bound_ctrl:1
	v_add_f32_dpp v18, v18, v18 quad_perm:[2,3,0,1] row_mask:0xf bank_mask:0xf bound_ctrl:1
	v_add_f32_dpp v19, v19, v19 quad_perm:[2,3,0,1] row_mask:0xf bank_mask:0xf bound_ctrl:1
	v_cmp_eq_u32_e64 s[2:3], 1, v125
	s_nop 1
	v_cndmask_b32_e64 v16, v16, v17, s[2:3]
	v_cmp_eq_u32_e64 s[2:3], 2, v125
	s_nop 1
	v_cndmask_b32_e64 v16, v16, v18, s[2:3]
	v_cmp_eq_u32_e64 s[2:3], 3, v125
	s_nop 1
	v_cndmask_b32_e64 v18, v16, v19, s[2:3]
	s_cmp_lg_u32 s49, 15
	s_cbranch_scc1 .Lscan_y_nofix
	v_lshl_add_u64 v[108:109], v[110:111], 0, v[108:109]
.Lscan_y_nofix:
	global_store_dword v[108:109], v18, off
	v_lshl_add_u64 v[108:109], v[112:113], 0, v[108:109]
	s_waitcnt vmcnt(17)
	s_waitcnt lgkmcnt(0)
	s_barrier

.Lscan_ld_steady_a:
	s_add_i32 s2, s49, -1
	s_lshl_b32 s3, s2, 14
	s_and_b32 s3, s3, 0x4000
	v_add_u32_e32 v4, s3, v126
	v_add_u32_e32 v8, s3, v127
	v_add_u32_e32 v16, s3, v128
	v_add_u32_e32 v20, s3, v129
	ds_read_b128 v[4:7], v4 offset:43008
	ds_read_b128 v[8:11], v8 offset:43008
	ds_read_b128 v[16:19], v16 offset:43008
	ds_read_b128 v[20:23], v20 offset:43008
	v_add_u32_e32 v38, s72, v91
	v_add_u32_e32 v95, v38, v92
	s_waitcnt vmcnt(19)
	v_lshlrev_b32_e32 v38, 16, v56
	v_and_b32_e32 v39, 0xffff0000, v56
	v_lshlrev_b32_e32 v40, 16, v57
	v_and_b32_e32 v41, 0xffff0000, v57
	ds_write_b128 v95, v[38:41] offset:4096
	s_waitcnt vmcnt(18)
	s_waitcnt vmcnt(17)
	s_waitcnt vmcnt(16)
	v_lshlrev_b32_e32 v38, 16, v58
	v_and_b32_e32 v39, 0xffff0000, v58
	v_lshlrev_b32_e32 v40, 16, v59
	v_and_b32_e32 v41, 0xffff0000, v59
	ds_write_b128 v95, v[38:41] offset:16384
	s_and_saveexec_b64 s[26:27], s[44:45]
	s_cbranch_execz .LBB0_1109
	v_lshlrev_b32_e32 v42, 2, v93
	v_lshlrev_b32_e32 v43, 2, v94
	v_add3_u32 v42, s72, v42, v43
	s_waitcnt vmcnt(15)
	v_lshlrev_b32_e32 v38, 16, v74
	v_and_b32_e32 v39, 0xffff0000, v74
	v_add_u32_e32 v42, 0x5000, v42
	v_lshlrev_b32_e32 v40, 16, v75
	v_and_b32_e32 v41, 0xffff0000, v75
	ds_write2_b32 v42, v38, v39 offset1:16
	ds_write2_b32 v42, v40, v41 offset0:32 offset1:48
	s_or_b64 exec, exec, s[26:27]
	s_cmpk_gt_u32 s49, 0x10b
	s_cbranch_scc0 .LBB0_1110

.LBB0_1161:
	s_waitcnt lgkmcnt(0)
	v_pk_add_f32 v[6:7], v[6:7], v[10:11]
	v_pk_add_f32 v[4:5], v[4:5], v[8:9]
	v_pk_add_f32 v[18:19], v[18:19], v[22:23]
	v_pk_add_f32 v[16:17], v[16:17], v[20:21]
	v_pk_add_f32 v[18:19], v[6:7], v[18:19]
	v_pk_add_f32 v[16:17], v[4:5], v[16:17]
	s_nop 1
	v_add_f32_dpp v16, v16, v16 quad_perm:[1,0,3,2] row_mask:0xf bank_mask:0xf bound_ctrl:1
	v_add_f32_dpp v17, v17, v17 quad_perm:[1,0,3,2] row_mask:0xf bank_mask:0xf bound_ctrl:1
	v_add_f32_dpp v18, v18, v18 quad_perm:[1,0,3,2] row_mask:0xf bank_mask:0xf bound_ctrl:1
	v_add_f32_dpp v19, v19, v19 quad_perm:[1,0,3,2] row_mask:0xf bank_mask:0xf bound_ctrl:1
	v_add_f32_dpp v16, v16, v16 quad_perm:[2,3,0,1] row_mask:0xf bank_mask:0xf bound_ctrl:1
	v_add_f32_dpp v17, v17, v17 quad_perm:[2,3,0,1] row_mask:0xf bank_mask:0xf bound_ctrl:1
	v_add_f32_dpp v18, v18, v18 quad_perm:[2,3,0,1] row_mask:0xf bank_mask:0xf bound_ctrl:1
	v_add_f32_dpp v19, v19, v19 quad_perm:[2,3,0,1] row_mask:0xf bank_mask:0xf bound_ctrl:1
	v_cmp_eq_u32_e64 s[2:3], 1, v125
	s_nop 1
	v_cndmask_b32_e64 v16, v16, v17, s[2:3]
	v_cmp_eq_u32_e64 s[2:3], 2, v125
	s_nop 1
	v_cndmask_b32_e64 v16, v16, v18, s[2:3]
	v_cmp_eq_u32_e64 s[2:3], 3, v125
	s_nop 1
	v_cndmask_b32_e64 v18, v16, v19, s[2:3]
	global_store_dword v[108:109], v18, off
	v_lshl_add_u64 v[108:109], v[112:113], 0, v[108:109]

.Lscan_ld_steady_b:
	s_lshl_b32 s3, s49, 14
	s_and_b32 s3, s3, 0x4000
	v_add_u32_e32 v4, s3, v126
	v_add_u32_e32 v8, s3, v127
	v_add_u32_e32 v16, s3, v128
	v_add_u32_e32 v20, s3, v129
	ds_read_b128 v[4:7], v4 offset:43008
	ds_read_b128 v[8:11], v8 offset:43008
	ds_read_b128 v[16:19], v16 offset:43008
	ds_read_b128 v[20:23], v20 offset:43008
	s_cmpk_lt_u32 s49, 0x10e
	s_cselect_b64 s[60:61], -1, 0
	s_cmpk_gt_u32 s49, 0x10d
	s_cbranch_scc1 .LBB0_1167
	s_bitcmp1_b32 s49, 0
	s_cselect_b32 s2, 0x5400, 0
	s_add_i32 s33, s2, 0
	v_add3_u32 v42, s33, v91, v92
	s_waitcnt vmcnt(19)
	v_lshlrev_b32_e32 v38, 16, v76
	v_and_b32_e32 v39, 0xffff0000, v76
	v_lshlrev_b32_e32 v40, 16, v77
	v_and_b32_e32 v41, 0xffff0000, v77
	ds_write_b128 v42, v[38:41] offset:4096
	s_waitcnt vmcnt(18)
	s_waitcnt vmcnt(17)
	s_waitcnt vmcnt(16)
	v_lshlrev_b32_e32 v38, 16, v78
	v_and_b32_e32 v39, 0xffff0000, v78
	v_lshlrev_b32_e32 v40, 16, v79
	v_and_b32_e32 v41, 0xffff0000, v79
	ds_write_b128 v42, v[38:41] offset:16384
	s_and_saveexec_b64 s[26:27], s[44:45]
	s_cbranch_execz .LBB0_1165
	v_lshlrev_b32_e32 v42, 2, v93
	v_lshlrev_b32_e32 v43, 2, v94
	v_add3_u32 v42, s33, v42, v43
	s_waitcnt vmcnt(15)
	v_lshlrev_b32_e32 v38, 16, v80
	v_and_b32_e32 v39, 0xffff0000, v80
	v_add_u32_e32 v42, 0x5000, v42
	v_lshlrev_b32_e32 v40, 16, v81
	v_and_b32_e32 v41, 0xffff0000, v81
	ds_write2_b32 v42, v38, v39 offset1:16
	ds_write2_b32 v42, v40, v41 offset0:32 offset1:48

.LBB0_1221:
	s_waitcnt lgkmcnt(0)
	v_pk_add_f32 v[6:7], v[6:7], v[10:11]
	v_pk_add_f32 v[4:5], v[4:5], v[8:9]
	v_pk_add_f32 v[18:19], v[18:19], v[22:23]
	v_pk_add_f32 v[16:17], v[16:17], v[20:21]
	v_pk_add_f32 v[18:19], v[6:7], v[18:19]
	v_pk_add_f32 v[16:17], v[4:5], v[16:17]
	s_nop 1
	v_add_f32_dpp v16, v16, v16 quad_perm:[1,0,3,2] row_mask:0xf bank_mask:0xf bound_ctrl:1
	v_add_f32_dpp v17, v17, v17 quad_perm:[1,0,3,2] row_mask:0xf bank_mask:0xf bound_ctrl:1
	v_add_f32_dpp v18, v18, v18 quad_perm:[1,0,3,2] row_mask:0xf bank_mask:0xf bound_ctrl:1
	v_add_f32_dpp v19, v19, v19 quad_perm:[1,0,3,2] row_mask:0xf bank_mask:0xf bound_ctrl:1
	v_add_f32_dpp v16, v16, v16 quad_perm:[2,3,0,1] row_mask:0xf bank_mask:0xf bound_ctrl:1
	v_add_f32_dpp v17, v17, v17 quad_perm:[2,3,0,1] row_mask:0xf bank_mask:0xf bound_ctrl:1
	v_add_f32_dpp v18, v18, v18 quad_perm:[2,3,0,1] row_mask:0xf bank_mask:0xf bound_ctrl:1
	v_add_f32_dpp v19, v19, v19 quad_perm:[2,3,0,1] row_mask:0xf bank_mask:0xf bound_ctrl:1
	s_andn2_b64 vcc, exec, s[60:61]
	v_cmp_eq_u32_e64 s[2:3], 1, v125
	s_nop 1
	v_cndmask_b32_e64 v16, v16, v17, s[2:3]
	v_cmp_eq_u32_e64 s[2:3], 2, v125
	s_nop 1
	v_cndmask_b32_e64 v16, v16, v18, s[2:3]
	v_cmp_eq_u32_e64 s[2:3], 3, v125
	s_nop 1
	v_cndmask_b32_e64 v18, v16, v19, s[2:3]
	global_store_dword v[108:109], v18, off
	v_lshl_add_u64 v[108:109], v[112:113], 0, v[108:109]
	s_waitcnt vmcnt(17)
	s_waitcnt lgkmcnt(0)
	s_barrier
	s_cmpk_lt_u32 s49, 6
	s_cbranch_scc1 .Lscan_ld_drain_c
	s_cmpk_lt_u32 s49, 0x109
	s_cbranch_scc1 .Lscan_ld_steady_c

.Lscan_ld_steady_c:
	s_cbranch_vccnz .LBB0_1105
	s_add_i32 s2, s49, 1
	s_lshl_b32 s3, s2, 14
	s_and_b32 s3, s3, 0x4000
	v_add_u32_e32 v4, s3, v126
	v_add_u32_e32 v8, s3, v127
	v_add_u32_e32 v16, s3, v128
	v_add_u32_e32 v20, s3, v129
	ds_read_b128 v[4:7], v4 offset:43008
	ds_read_b128 v[8:11], v8 offset:43008
	ds_read_b128 v[16:19], v16 offset:43008
	ds_read_b128 v[20:23], v20 offset:43008
	s_cmpk_eq_i32 s49, 0x10d
	s_cbranch_scc1 .LBB0_1226
	s_waitcnt vmcnt(19)
	v_lshlrev_b32_e32 v38, 16, v82
	v_and_b32_e32 v39, 0xffff0000, v82
	v_lshlrev_b32_e32 v40, 16, v83
	v_and_b32_e32 v41, 0xffff0000, v83
	ds_write_b128 v95, v[38:41] offset:4096
	s_waitcnt vmcnt(18)
	s_waitcnt vmcnt(17)
	s_waitcnt vmcnt(16)
	v_lshlrev_b32_e32 v38, 16, v84
	v_and_b32_e32 v39, 0xffff0000, v84
	v_lshlrev_b32_e32 v40, 16, v85
	v_and_b32_e32 v41, 0xffff0000, v85
	ds_write_b128 v95, v[38:41] offset:16384
	s_and_saveexec_b64 s[26:27], s[44:45]
	s_cbranch_execz .LBB0_1225
	v_lshlrev_b32_e32 v42, 2, v93
	v_lshlrev_b32_e32 v43, 2, v94
	v_add3_u32 v42, s72, v42, v43
	s_waitcnt vmcnt(15)
	v_lshlrev_b32_e32 v38, 16, v86
	v_and_b32_e32 v39, 0xffff0000, v86
	v_add_u32_e32 v42, 0x5000, v42
	v_lshlrev_b32_e32 v40, 16, v87
	v_and_b32_e32 v41, 0xffff0000, v87
	ds_write2_b32 v42, v38, v39 offset1:16
	ds_write2_b32 v42, v40, v41 offset0:32 offset1:48

.LBB0_1266:
	s_add_i32 s2, s49, 1
	s_lshl_b32 s3, s2, 14
	s_and_b32 s3, s3, 0x4000
	s_branch .LBB0_1104
